# out-proj/down-proj K-loops: last iteration split off without the DMA loads that only feed a following iteration
# speedup vs baseline: 1.0010x; 1.0010x over previous
.LBB0_774:
	s_add_u32 s46, s30, 0xfffc0080
	s_addc_u32 s47, s31, -1
	s_add_i32 s62, 0, 0x10000
	s_cmp_eq_u32 s61, 12
	s_cselect_b32 s49, s14, s47
	s_cselect_b32 s48, s15, s46
	s_cselect_b32 s47, s23, s60
	s_cselect_b32 s46, s25, s59
	s_add_i32 s64, 0, 0x14000
	v_add_u32_e32 v144, s62, v192
	v_add_u32_e32 v166, s64, v192
	ds_read_b128 v[132:135], v144
	ds_read_b128 v[136:139], v144 offset:1024
	ds_read_b128 v[140:143], v144 offset:2048
	ds_read_b128 v[144:147], v144 offset:3072
	ds_read_b128 v[148:151], v166
	ds_read_b128 v[152:155], v166 offset:1024
	ds_read_b128 v[176:179], v166 offset:2048
	ds_read_b128 v[180:183], v166 offset:3072
	v_lshl_add_u64 v[166:167], s[30:31], 0, v[162:163]
	s_add_i32 m0, s53, 0xc000
	ds_read_b128 v[184:187], v194
	ds_read_b128 v[188:191], v194 offset:1024
	ds_read_b128 v[196:199], v194 offset:2048
	ds_read_b128 v[200:203], v194 offset:3072
	ds_read_b128 v[204:207], v194 offset:4096
	ds_read_b128 v[208:211], v194 offset:5120
	ds_read_b128 v[234:237], v194 offset:6144
	ds_read_b128 v[238:241], v194 offset:7168
	global_load_lds_dwordx4 v[166:167], off
	v_lshl_add_u64 v[166:167], s[30:31], 0, v[164:165]
	s_add_i32 m0, s53, 0xe000
	s_nop 0
	global_load_lds_dwordx4 v[166:167], off
	s_waitcnt vmcnt(8)
	s_waitcnt lgkmcnt(0)
	s_barrier
	s_setprio 1
	s_waitcnt lgkmcnt(0)
	v_mfma_f32_16x16x32_bf16 v[128:131], v[132:135], v[184:187], v[128:131]
	v_mfma_f32_16x16x32_bf16 v[124:127], v[140:143], v[184:187], v[124:127]
	v_mfma_f32_16x16x32_bf16 v[112:115], v[132:135], v[196:199], v[112:115]
	v_mfma_f32_16x16x32_bf16 v[108:111], v[140:143], v[196:199], v[108:111]
	v_mfma_f32_16x16x32_bf16 v[96:99], v[132:135], v[204:207], v[96:99]
	v_mfma_f32_16x16x32_bf16 v[92:95], v[140:143], v[204:207], v[92:95]
	v_mfma_f32_16x16x32_bf16 v[80:83], v[132:135], v[234:237], v[80:83]
	v_mfma_f32_16x16x32_bf16 v[76:79], v[140:143], v[234:237], v[76:79]
	v_mfma_f32_16x16x32_bf16 v[128:131], v[136:139], v[188:191], v[128:131]
	v_mfma_f32_16x16x32_bf16 v[124:127], v[144:147], v[188:191], v[124:127]
	v_mfma_f32_16x16x32_bf16 v[112:115], v[136:139], v[200:203], v[112:115]
	v_mfma_f32_16x16x32_bf16 v[108:111], v[144:147], v[200:203], v[108:111]
	v_mfma_f32_16x16x32_bf16 v[96:99], v[136:139], v[208:211], v[96:99]
	v_mfma_f32_16x16x32_bf16 v[92:95], v[144:147], v[208:211], v[92:95]
	v_mfma_f32_16x16x32_bf16 v[80:83], v[136:139], v[238:241], v[80:83]
	v_mfma_f32_16x16x32_bf16 v[76:79], v[144:147], v[238:241], v[76:79]
	s_setprio 0
	s_setprio 1
	v_mfma_f32_16x16x32_bf16 v[120:123], v[148:151], v[184:187], v[120:123]
	v_mfma_f32_16x16x32_bf16 v[116:119], v[176:179], v[184:187], v[116:119]
	v_mfma_f32_16x16x32_bf16 v[104:107], v[148:151], v[196:199], v[104:107]
	v_mfma_f32_16x16x32_bf16 v[100:103], v[176:179], v[196:199], v[100:103]
	v_mfma_f32_16x16x32_bf16 v[88:91], v[148:151], v[204:207], v[88:91]
	v_mfma_f32_16x16x32_bf16 v[84:87], v[176:179], v[204:207], v[84:87]
	v_mfma_f32_16x16x32_bf16 v[72:75], v[148:151], v[234:237], v[72:75]
	v_mfma_f32_16x16x32_bf16 v[68:71], v[176:179], v[234:237], v[68:71]
	v_mfma_f32_16x16x32_bf16 v[120:123], v[152:155], v[188:191], v[120:123]
	v_mfma_f32_16x16x32_bf16 v[116:119], v[180:183], v[188:191], v[116:119]
	v_mfma_f32_16x16x32_bf16 v[104:107], v[152:155], v[200:203], v[104:107]
	v_mfma_f32_16x16x32_bf16 v[100:103], v[180:183], v[200:203], v[100:103]
	v_mfma_f32_16x16x32_bf16 v[88:91], v[152:155], v[208:211], v[88:91]
	v_mfma_f32_16x16x32_bf16 v[84:87], v[180:183], v[208:211], v[84:87]
	v_mfma_f32_16x16x32_bf16 v[72:75], v[152:155], v[238:241], v[72:75]
	v_mfma_f32_16x16x32_bf16 v[68:71], v[180:183], v[238:241], v[68:71]
	s_setprio 0
	s_barrier
	s_add_i32 s62, s62, s52
	v_lshl_add_u64 v[166:167], s[46:47], 0, v[2:3]
	s_mov_b32 m0, s62
	ds_read_b128 v[184:187], v194 offset:16384
	ds_read_b128 v[188:191], v194 offset:17408
	ds_read_b128 v[196:199], v194 offset:18432
	ds_read_b128 v[200:203], v194 offset:19456
	ds_read_b128 v[204:207], v194 offset:20480
	ds_read_b128 v[208:211], v194 offset:21504
	ds_read_b128 v[234:237], v194 offset:22528
	ds_read_b128 v[238:241], v194 offset:23552
	global_load_lds_dwordx4 v[166:167], off
	s_add_i32 m0, s62, 0x2000
	s_add_u32 s62, s46, 0x40000
	v_lshl_add_u64 v[212:213], s[46:47], 0, v[156:157]
	s_addc_u32 s63, s47, 0
	s_add_i32 s64, s64, s52
	global_load_lds_dwordx4 v[212:213], off
	v_lshl_add_u64 v[242:243], s[62:63], 0, v[2:3]
	s_mov_b32 m0, s64
	v_lshl_add_u64 v[244:245], s[48:49], 0, v[158:159]
	global_load_lds_dwordx4 v[242:243], off
	v_lshl_add_u64 v[242:243], s[62:63], 0, v[156:157]
	s_add_i32 m0, s64, 0x2000
	s_nop 0
	global_load_lds_dwordx4 v[242:243], off
	v_lshl_add_u64 v[242:243], s[48:49], 0, v[160:161]
	s_mov_b32 m0, s53
	s_nop 0
	global_load_lds_dwordx4 v[242:243], off
	s_mov_b32 m0, s54
	s_nop 0
	global_load_lds_dwordx4 v[244:245], off
	s_waitcnt vmcnt(8)
	s_waitcnt lgkmcnt(0)
	s_barrier
	s_setprio 1
	s_waitcnt lgkmcnt(0)
	v_mfma_f32_16x16x32_bf16 v[64:67], v[132:135], v[184:187], v[64:67]
	v_mfma_f32_16x16x32_bf16 v[60:63], v[140:143], v[184:187], v[60:63]
	v_mfma_f32_16x16x32_bf16 v[48:51], v[132:135], v[196:199], v[48:51]
	v_mfma_f32_16x16x32_bf16 v[44:47], v[140:143], v[196:199], v[44:47]
	v_mfma_f32_16x16x32_bf16 v[32:35], v[132:135], v[204:207], v[32:35]
	v_mfma_f32_16x16x32_bf16 v[28:31], v[140:143], v[204:207], v[28:31]
	v_mfma_f32_16x16x32_bf16 v[16:19], v[132:135], v[234:237], v[16:19]
	v_mfma_f32_16x16x32_bf16 v[12:15], v[140:143], v[234:237], v[12:15]
	v_mfma_f32_16x16x32_bf16 v[64:67], v[136:139], v[188:191], v[64:67]
	v_mfma_f32_16x16x32_bf16 v[60:63], v[144:147], v[188:191], v[60:63]
	v_mfma_f32_16x16x32_bf16 v[48:51], v[136:139], v[200:203], v[48:51]
	v_mfma_f32_16x16x32_bf16 v[44:47], v[144:147], v[200:203], v[44:47]
	v_mfma_f32_16x16x32_bf16 v[32:35], v[136:139], v[208:211], v[32:35]
	v_mfma_f32_16x16x32_bf16 v[28:31], v[144:147], v[208:211], v[28:31]
	v_mfma_f32_16x16x32_bf16 v[16:19], v[136:139], v[238:241], v[16:19]
	v_mfma_f32_16x16x32_bf16 v[12:15], v[144:147], v[238:241], v[12:15]
	s_setprio 0
	s_setprio 1
	v_mfma_f32_16x16x32_bf16 v[56:59], v[148:151], v[184:187], v[56:59]
	v_mfma_f32_16x16x32_bf16 v[52:55], v[176:179], v[184:187], v[52:55]
	v_mfma_f32_16x16x32_bf16 v[40:43], v[148:151], v[196:199], v[40:43]
	v_mfma_f32_16x16x32_bf16 v[36:39], v[176:179], v[196:199], v[36:39]
	v_mfma_f32_16x16x32_bf16 v[24:27], v[148:151], v[204:207], v[24:27]
	v_mfma_f32_16x16x32_bf16 v[20:23], v[176:179], v[204:207], v[20:23]
	v_mfma_f32_16x16x32_bf16 v[8:11], v[148:151], v[234:237], v[8:11]
	v_mfma_f32_16x16x32_bf16 v[4:7], v[176:179], v[234:237], v[4:7]
	v_mfma_f32_16x16x32_bf16 v[56:59], v[152:155], v[188:191], v[56:59]
	v_mfma_f32_16x16x32_bf16 v[52:55], v[180:183], v[188:191], v[52:55]
	v_mfma_f32_16x16x32_bf16 v[40:43], v[152:155], v[200:203], v[40:43]
	v_mfma_f32_16x16x32_bf16 v[36:39], v[180:183], v[200:203], v[36:39]
	v_mfma_f32_16x16x32_bf16 v[24:27], v[152:155], v[208:211], v[24:27]
	v_mfma_f32_16x16x32_bf16 v[20:23], v[180:183], v[208:211], v[20:23]
	v_mfma_f32_16x16x32_bf16 v[8:11], v[152:155], v[238:241], v[8:11]
	v_mfma_f32_16x16x32_bf16 v[4:7], v[180:183], v[238:241], v[4:7]
	s_setprio 0
	s_barrier
	s_add_i32 s62, 0, 0x18000
	s_add_i32 s63, 0, 0x1c000
	v_add_u32_e32 v144, s62, v192
	v_add_u32_e32 v180, s63, v192
	ds_read_b128 v[132:135], v144
	ds_read_b128 v[136:139], v144 offset:1024
	ds_read_b128 v[140:143], v144 offset:2048
	ds_read_b128 v[144:147], v144 offset:3072
	ds_read_b128 v[148:151], v180
	ds_read_b128 v[152:155], v180 offset:1024
	ds_read_b128 v[176:179], v180 offset:2048
	ds_read_b128 v[180:183], v180 offset:3072
	s_add_u32 s48, s48, 0x40000
	s_addc_u32 s49, s49, 0
	s_mov_b32 m0, s55
	v_lshl_add_u64 v[246:247], s[48:49], 0, v[160:161]
	ds_read_b128 v[184:187], v194 offset:32768
	ds_read_b128 v[188:191], v194 offset:33792
	ds_read_b128 v[196:199], v194 offset:34816
	ds_read_b128 v[200:203], v194 offset:35840
	ds_read_b128 v[204:207], v194 offset:36864
	ds_read_b128 v[208:211], v194 offset:37888
	ds_read_b128 v[234:237], v194 offset:38912
	ds_read_b128 v[238:241], v194 offset:39936
	global_load_lds_dwordx4 v[246:247], off
	v_lshl_add_u64 v[246:247], s[48:49], 0, v[158:159]
	s_mov_b32 m0, s56
	s_nop 0
	global_load_lds_dwordx4 v[246:247], off
	s_waitcnt vmcnt(8)
	s_waitcnt lgkmcnt(0)
	s_barrier
	s_setprio 1
	s_waitcnt lgkmcnt(0)
	v_mfma_f32_16x16x32_bf16 v[128:131], v[132:135], v[184:187], v[128:131]
	v_mfma_f32_16x16x32_bf16 v[124:127], v[140:143], v[184:187], v[124:127]
	v_mfma_f32_16x16x32_bf16 v[112:115], v[132:135], v[196:199], v[112:115]
	v_mfma_f32_16x16x32_bf16 v[108:111], v[140:143], v[196:199], v[108:111]
	v_mfma_f32_16x16x32_bf16 v[96:99], v[132:135], v[204:207], v[96:99]
	v_mfma_f32_16x16x32_bf16 v[92:95], v[140:143], v[204:207], v[92:95]
	v_mfma_f32_16x16x32_bf16 v[80:83], v[132:135], v[234:237], v[80:83]
	v_mfma_f32_16x16x32_bf16 v[76:79], v[140:143], v[234:237], v[76:79]
	v_mfma_f32_16x16x32_bf16 v[128:131], v[136:139], v[188:191], v[128:131]
	v_mfma_f32_16x16x32_bf16 v[124:127], v[144:147], v[188:191], v[124:127]
	v_mfma_f32_16x16x32_bf16 v[112:115], v[136:139], v[200:203], v[112:115]
	v_mfma_f32_16x16x32_bf16 v[108:111], v[144:147], v[200:203], v[108:111]
	v_mfma_f32_16x16x32_bf16 v[96:99], v[136:139], v[208:211], v[96:99]
	v_mfma_f32_16x16x32_bf16 v[92:95], v[144:147], v[208:211], v[92:95]
	v_mfma_f32_16x16x32_bf16 v[80:83], v[136:139], v[238:241], v[80:83]
	v_mfma_f32_16x16x32_bf16 v[76:79], v[144:147], v[238:241], v[76:79]
	s_setprio 0
	s_setprio 1
	v_mfma_f32_16x16x32_bf16 v[120:123], v[148:151], v[184:187], v[120:123]
	v_mfma_f32_16x16x32_bf16 v[116:119], v[176:179], v[184:187], v[116:119]
	v_mfma_f32_16x16x32_bf16 v[104:107], v[148:151], v[196:199], v[104:107]
	v_mfma_f32_16x16x32_bf16 v[100:103], v[176:179], v[196:199], v[100:103]
	v_mfma_f32_16x16x32_bf16 v[88:91], v[148:151], v[204:207], v[88:91]
	v_mfma_f32_16x16x32_bf16 v[84:87], v[176:179], v[204:207], v[84:87]
	v_mfma_f32_16x16x32_bf16 v[72:75], v[148:151], v[234:237], v[72:75]
	v_mfma_f32_16x16x32_bf16 v[68:71], v[176:179], v[234:237], v[68:71]
	v_mfma_f32_16x16x32_bf16 v[120:123], v[152:155], v[188:191], v[120:123]
	v_mfma_f32_16x16x32_bf16 v[116:119], v[180:183], v[188:191], v[116:119]
	v_mfma_f32_16x16x32_bf16 v[104:107], v[152:155], v[200:203], v[104:107]
	v_mfma_f32_16x16x32_bf16 v[100:103], v[180:183], v[200:203], v[100:103]
	v_mfma_f32_16x16x32_bf16 v[88:91], v[152:155], v[208:211], v[88:91]
	v_mfma_f32_16x16x32_bf16 v[84:87], v[180:183], v[208:211], v[84:87]
	v_mfma_f32_16x16x32_bf16 v[72:75], v[152:155], v[238:241], v[72:75]
	v_mfma_f32_16x16x32_bf16 v[68:71], v[180:183], v[238:241], v[68:71]
	s_setprio 0
	s_barrier
	s_add_i32 s48, s62, s52
	v_lshl_add_u64 v[166:167], v[166:167], 0, s[16:17]
	s_mov_b32 m0, s48
	ds_read_b128 v[184:187], v194 offset:49152
	ds_read_b128 v[188:191], v194 offset:50176
	ds_read_b128 v[196:199], v194 offset:51200
	ds_read_b128 v[200:203], v194 offset:52224
	ds_read_b128 v[204:207], v194 offset:53248
	ds_read_b128 v[208:211], v194 offset:54272
	ds_read_b128 v[234:237], v194 offset:55296
	ds_read_b128 v[238:241], v194 offset:56320
	global_load_lds_dwordx4 v[166:167], off
	s_add_i32 m0, s48, 0x2000
	s_add_u32 s46, s46, 0x40080
	v_lshl_add_u64 v[166:167], v[212:213], 0, s[16:17]
	s_addc_u32 s47, s47, 0
	s_add_i32 s48, s63, s52
	global_load_lds_dwordx4 v[166:167], off
	v_lshl_add_u64 v[166:167], s[46:47], 0, v[2:3]
	s_mov_b32 m0, s48
	s_nop 0
	global_load_lds_dwordx4 v[166:167], off
	v_lshl_add_u64 v[166:167], s[46:47], 0, v[156:157]
	s_add_i32 m0, s48, 0x2000
	s_nop 0
	global_load_lds_dwordx4 v[166:167], off
	v_lshl_add_u64 v[166:167], v[242:243], 0, s[16:17]
	s_mov_b32 m0, s34
	s_nop 0
	global_load_lds_dwordx4 v[166:167], off
	v_lshl_add_u64 v[166:167], v[244:245], 0, s[16:17]
	s_mov_b32 m0, s57
	s_nop 0
	global_load_lds_dwordx4 v[166:167], off
	s_waitcnt vmcnt(8)
	s_waitcnt lgkmcnt(0)
	s_barrier
	s_setprio 1
	s_waitcnt lgkmcnt(0)
	v_mfma_f32_16x16x32_bf16 v[64:67], v[132:135], v[184:187], v[64:67]
	v_mfma_f32_16x16x32_bf16 v[60:63], v[140:143], v[184:187], v[60:63]
	v_mfma_f32_16x16x32_bf16 v[48:51], v[132:135], v[196:199], v[48:51]
	v_mfma_f32_16x16x32_bf16 v[44:47], v[140:143], v[196:199], v[44:47]
	v_mfma_f32_16x16x32_bf16 v[32:35], v[132:135], v[204:207], v[32:35]
	v_mfma_f32_16x16x32_bf16 v[28:31], v[140:143], v[204:207], v[28:31]
	v_mfma_f32_16x16x32_bf16 v[16:19], v[132:135], v[234:237], v[16:19]
	v_mfma_f32_16x16x32_bf16 v[12:15], v[140:143], v[234:237], v[12:15]
	v_mfma_f32_16x16x32_bf16 v[64:67], v[136:139], v[188:191], v[64:67]
	v_mfma_f32_16x16x32_bf16 v[60:63], v[144:147], v[188:191], v[60:63]
	v_mfma_f32_16x16x32_bf16 v[48:51], v[136:139], v[200:203], v[48:51]
	v_mfma_f32_16x16x32_bf16 v[44:47], v[144:147], v[200:203], v[44:47]
	v_mfma_f32_16x16x32_bf16 v[32:35], v[136:139], v[208:211], v[32:35]
	v_mfma_f32_16x16x32_bf16 v[28:31], v[144:147], v[208:211], v[28:31]
	v_mfma_f32_16x16x32_bf16 v[16:19], v[136:139], v[238:241], v[16:19]
	v_mfma_f32_16x16x32_bf16 v[12:15], v[144:147], v[238:241], v[12:15]
	s_setprio 0
	s_setprio 1
	v_mfma_f32_16x16x32_bf16 v[56:59], v[148:151], v[184:187], v[56:59]
	v_mfma_f32_16x16x32_bf16 v[52:55], v[176:179], v[184:187], v[52:55]
	v_mfma_f32_16x16x32_bf16 v[40:43], v[148:151], v[196:199], v[40:43]
	v_mfma_f32_16x16x32_bf16 v[36:39], v[176:179], v[196:199], v[36:39]
	v_mfma_f32_16x16x32_bf16 v[24:27], v[148:151], v[204:207], v[24:27]
	v_mfma_f32_16x16x32_bf16 v[20:23], v[176:179], v[204:207], v[20:23]
	v_mfma_f32_16x16x32_bf16 v[8:11], v[148:151], v[234:237], v[8:11]
	v_mfma_f32_16x16x32_bf16 v[4:7], v[176:179], v[234:237], v[4:7]
	v_mfma_f32_16x16x32_bf16 v[56:59], v[152:155], v[188:191], v[56:59]
	v_mfma_f32_16x16x32_bf16 v[52:55], v[180:183], v[188:191], v[52:55]
	v_mfma_f32_16x16x32_bf16 v[40:43], v[152:155], v[200:203], v[40:43]
	v_mfma_f32_16x16x32_bf16 v[36:39], v[180:183], v[200:203], v[36:39]
	v_mfma_f32_16x16x32_bf16 v[24:27], v[152:155], v[208:211], v[24:27]
	v_mfma_f32_16x16x32_bf16 v[20:23], v[180:183], v[208:211], v[20:23]
	v_mfma_f32_16x16x32_bf16 v[8:11], v[152:155], v[238:241], v[8:11]
	v_mfma_f32_16x16x32_bf16 v[4:7], v[180:183], v[238:241], v[4:7]
	s_setprio 0
	s_barrier
	s_add_i32 s61, s61, 2
	s_add_u32 s30, s30, 0x100
	s_addc_u32 s31, s31, 0
	s_add_u32 s59, s59, 0x100
	s_addc_u32 s60, s60, 0
	s_cmp_gt_u32 s61, 11
	s_cbranch_scc0 .LBB0_774
	s_add_u32 s46, s30, 0xfffc0080
	s_addc_u32 s47, s31, -1
	s_add_i32 s62, 0, 0x10000
	s_cmp_eq_u32 s61, 12
	s_cselect_b32 s49, s14, s47
	s_cselect_b32 s48, s15, s46
	s_cselect_b32 s47, s23, s60
	s_cselect_b32 s46, s25, s59
	s_add_i32 s64, 0, 0x14000
	v_add_u32_e32 v144, s62, v192
	v_add_u32_e32 v166, s64, v192
	ds_read_b128 v[132:135], v144
	ds_read_b128 v[136:139], v144 offset:1024
	ds_read_b128 v[140:143], v144 offset:2048
	ds_read_b128 v[144:147], v144 offset:3072
	ds_read_b128 v[148:151], v166
	ds_read_b128 v[152:155], v166 offset:1024
	ds_read_b128 v[176:179], v166 offset:2048
	ds_read_b128 v[180:183], v166 offset:3072
	v_lshl_add_u64 v[166:167], s[30:31], 0, v[162:163]
	s_add_i32 m0, s53, 0xc000
	ds_read_b128 v[184:187], v194
	ds_read_b128 v[188:191], v194 offset:1024
	ds_read_b128 v[196:199], v194 offset:2048
	ds_read_b128 v[200:203], v194 offset:3072
	ds_read_b128 v[204:207], v194 offset:4096
	ds_read_b128 v[208:211], v194 offset:5120
	ds_read_b128 v[234:237], v194 offset:6144
	ds_read_b128 v[238:241], v194 offset:7168
	global_load_lds_dwordx4 v[166:167], off
	v_lshl_add_u64 v[166:167], s[30:31], 0, v[164:165]
	s_add_i32 m0, s53, 0xe000
	s_nop 0
	global_load_lds_dwordx4 v[166:167], off
	s_waitcnt vmcnt(8)
	s_waitcnt lgkmcnt(0)
	s_barrier
	s_setprio 1
	s_waitcnt lgkmcnt(0)
	v_mfma_f32_16x16x32_bf16 v[128:131], v[132:135], v[184:187], v[128:131]
	v_mfma_f32_16x16x32_bf16 v[124:127], v[140:143], v[184:187], v[124:127]
	v_mfma_f32_16x16x32_bf16 v[112:115], v[132:135], v[196:199], v[112:115]
	v_mfma_f32_16x16x32_bf16 v[108:111], v[140:143], v[196:199], v[108:111]
	v_mfma_f32_16x16x32_bf16 v[96:99], v[132:135], v[204:207], v[96:99]
	v_mfma_f32_16x16x32_bf16 v[92:95], v[140:143], v[204:207], v[92:95]
	v_mfma_f32_16x16x32_bf16 v[80:83], v[132:135], v[234:237], v[80:83]
	v_mfma_f32_16x16x32_bf16 v[76:79], v[140:143], v[234:237], v[76:79]
	v_mfma_f32_16x16x32_bf16 v[128:131], v[136:139], v[188:191], v[128:131]
	v_mfma_f32_16x16x32_bf16 v[124:127], v[144:147], v[188:191], v[124:127]
	v_mfma_f32_16x16x32_bf16 v[112:115], v[136:139], v[200:203], v[112:115]
	v_mfma_f32_16x16x32_bf16 v[108:111], v[144:147], v[200:203], v[108:111]
	v_mfma_f32_16x16x32_bf16 v[96:99], v[136:139], v[208:211], v[96:99]
	v_mfma_f32_16x16x32_bf16 v[92:95], v[144:147], v[208:211], v[92:95]
	v_mfma_f32_16x16x32_bf16 v[80:83], v[136:139], v[238:241], v[80:83]
	v_mfma_f32_16x16x32_bf16 v[76:79], v[144:147], v[238:241], v[76:79]
	s_setprio 0
	s_setprio 1
	v_mfma_f32_16x16x32_bf16 v[120:123], v[148:151], v[184:187], v[120:123]
	v_mfma_f32_16x16x32_bf16 v[116:119], v[176:179], v[184:187], v[116:119]
	v_mfma_f32_16x16x32_bf16 v[104:107], v[148:151], v[196:199], v[104:107]
	v_mfma_f32_16x16x32_bf16 v[100:103], v[176:179], v[196:199], v[100:103]
	v_mfma_f32_16x16x32_bf16 v[88:91], v[148:151], v[204:207], v[88:91]
	v_mfma_f32_16x16x32_bf16 v[84:87], v[176:179], v[204:207], v[84:87]
	v_mfma_f32_16x16x32_bf16 v[72:75], v[148:151], v[234:237], v[72:75]
	v_mfma_f32_16x16x32_bf16 v[68:71], v[176:179], v[234:237], v[68:71]
	v_mfma_f32_16x16x32_bf16 v[120:123], v[152:155], v[188:191], v[120:123]
	v_mfma_f32_16x16x32_bf16 v[116:119], v[180:183], v[188:191], v[116:119]
	v_mfma_f32_16x16x32_bf16 v[104:107], v[152:155], v[200:203], v[104:107]
	v_mfma_f32_16x16x32_bf16 v[100:103], v[180:183], v[200:203], v[100:103]
	v_mfma_f32_16x16x32_bf16 v[88:91], v[152:155], v[208:211], v[88:91]
	v_mfma_f32_16x16x32_bf16 v[84:87], v[180:183], v[208:211], v[84:87]
	v_mfma_f32_16x16x32_bf16 v[72:75], v[152:155], v[238:241], v[72:75]
	v_mfma_f32_16x16x32_bf16 v[68:71], v[180:183], v[238:241], v[68:71]
	s_setprio 0
	s_barrier
	s_add_i32 s62, s62, s52
	v_lshl_add_u64 v[166:167], s[46:47], 0, v[2:3]
	s_mov_b32 m0, s62
	ds_read_b128 v[184:187], v194 offset:16384
	ds_read_b128 v[188:191], v194 offset:17408
	ds_read_b128 v[196:199], v194 offset:18432
	ds_read_b128 v[200:203], v194 offset:19456
	ds_read_b128 v[204:207], v194 offset:20480
	ds_read_b128 v[208:211], v194 offset:21504
	ds_read_b128 v[234:237], v194 offset:22528
	ds_read_b128 v[238:241], v194 offset:23552
	s_add_i32 m0, s62, 0x2000
	s_add_u32 s62, s46, 0x40000
	v_lshl_add_u64 v[212:213], s[46:47], 0, v[156:157]
	s_addc_u32 s63, s47, 0
	s_add_i32 s64, s64, s52
	v_lshl_add_u64 v[242:243], s[62:63], 0, v[2:3]
	s_mov_b32 m0, s64
	v_lshl_add_u64 v[244:245], s[48:49], 0, v[158:159]
	v_lshl_add_u64 v[242:243], s[62:63], 0, v[156:157]
	s_add_i32 m0, s64, 0x2000
	s_nop 0
	v_lshl_add_u64 v[242:243], s[48:49], 0, v[160:161]
	s_mov_b32 m0, s53
	s_nop 0
	s_mov_b32 m0, s54
	s_nop 0
	s_waitcnt vmcnt(2)
	s_waitcnt lgkmcnt(0)
	s_barrier
	s_setprio 1
	s_waitcnt lgkmcnt(0)
	v_mfma_f32_16x16x32_bf16 v[64:67], v[132:135], v[184:187], v[64:67]
	v_mfma_f32_16x16x32_bf16 v[60:63], v[140:143], v[184:187], v[60:63]
	v_mfma_f32_16x16x32_bf16 v[48:51], v[132:135], v[196:199], v[48:51]
	v_mfma_f32_16x16x32_bf16 v[44:47], v[140:143], v[196:199], v[44:47]
	v_mfma_f32_16x16x32_bf16 v[32:35], v[132:135], v[204:207], v[32:35]
	v_mfma_f32_16x16x32_bf16 v[28:31], v[140:143], v[204:207], v[28:31]
	v_mfma_f32_16x16x32_bf16 v[16:19], v[132:135], v[234:237], v[16:19]
	v_mfma_f32_16x16x32_bf16 v[12:15], v[140:143], v[234:237], v[12:15]
	v_mfma_f32_16x16x32_bf16 v[64:67], v[136:139], v[188:191], v[64:67]
	v_mfma_f32_16x16x32_bf16 v[60:63], v[144:147], v[188:191], v[60:63]
	v_mfma_f32_16x16x32_bf16 v[48:51], v[136:139], v[200:203], v[48:51]
	v_mfma_f32_16x16x32_bf16 v[44:47], v[144:147], v[200:203], v[44:47]
	v_mfma_f32_16x16x32_bf16 v[32:35], v[136:139], v[208:211], v[32:35]
	v_mfma_f32_16x16x32_bf16 v[28:31], v[144:147], v[208:211], v[28:31]
	v_mfma_f32_16x16x32_bf16 v[16:19], v[136:139], v[238:241], v[16:19]
	v_mfma_f32_16x16x32_bf16 v[12:15], v[144:147], v[238:241], v[12:15]
	s_setprio 0
	s_setprio 1
	v_mfma_f32_16x16x32_bf16 v[56:59], v[148:151], v[184:187], v[56:59]
	v_mfma_f32_16x16x32_bf16 v[52:55], v[176:179], v[184:187], v[52:55]
	v_mfma_f32_16x16x32_bf16 v[40:43], v[148:151], v[196:199], v[40:43]
	v_mfma_f32_16x16x32_bf16 v[36:39], v[176:179], v[196:199], v[36:39]
	v_mfma_f32_16x16x32_bf16 v[24:27], v[148:151], v[204:207], v[24:27]
	v_mfma_f32_16x16x32_bf16 v[20:23], v[176:179], v[204:207], v[20:23]
	v_mfma_f32_16x16x32_bf16 v[8:11], v[148:151], v[234:237], v[8:11]
	v_mfma_f32_16x16x32_bf16 v[4:7], v[176:179], v[234:237], v[4:7]
	v_mfma_f32_16x16x32_bf16 v[56:59], v[152:155], v[188:191], v[56:59]
	v_mfma_f32_16x16x32_bf16 v[52:55], v[180:183], v[188:191], v[52:55]
	v_mfma_f32_16x16x32_bf16 v[40:43], v[152:155], v[200:203], v[40:43]
	v_mfma_f32_16x16x32_bf16 v[36:39], v[180:183], v[200:203], v[36:39]
	v_mfma_f32_16x16x32_bf16 v[24:27], v[152:155], v[208:211], v[24:27]
	v_mfma_f32_16x16x32_bf16 v[20:23], v[180:183], v[208:211], v[20:23]
	v_mfma_f32_16x16x32_bf16 v[8:11], v[152:155], v[238:241], v[8:11]
	v_mfma_f32_16x16x32_bf16 v[4:7], v[180:183], v[238:241], v[4:7]
	s_setprio 0
	s_barrier
	s_add_i32 s62, 0, 0x18000
	s_add_i32 s63, 0, 0x1c000
	v_add_u32_e32 v144, s62, v192
	v_add_u32_e32 v180, s63, v192
	ds_read_b128 v[132:135], v144
	ds_read_b128 v[136:139], v144 offset:1024
	ds_read_b128 v[140:143], v144 offset:2048
	ds_read_b128 v[144:147], v144 offset:3072
	ds_read_b128 v[148:151], v180
	ds_read_b128 v[152:155], v180 offset:1024
	ds_read_b128 v[176:179], v180 offset:2048
	ds_read_b128 v[180:183], v180 offset:3072
	s_add_u32 s48, s48, 0x40000
	s_addc_u32 s49, s49, 0
	s_mov_b32 m0, s55
	v_lshl_add_u64 v[246:247], s[48:49], 0, v[160:161]
	ds_read_b128 v[184:187], v194 offset:32768
	ds_read_b128 v[188:191], v194 offset:33792
	ds_read_b128 v[196:199], v194 offset:34816
	ds_read_b128 v[200:203], v194 offset:35840
	ds_read_b128 v[204:207], v194 offset:36864
	ds_read_b128 v[208:211], v194 offset:37888
	ds_read_b128 v[234:237], v194 offset:38912
	ds_read_b128 v[238:241], v194 offset:39936
	v_lshl_add_u64 v[246:247], s[48:49], 0, v[158:159]
	s_mov_b32 m0, s56
	s_nop 0
	s_waitcnt vmcnt(0)
	s_waitcnt lgkmcnt(0)
	s_barrier
	s_setprio 1
	s_waitcnt lgkmcnt(0)
	v_mfma_f32_16x16x32_bf16 v[128:131], v[132:135], v[184:187], v[128:131]
	v_mfma_f32_16x16x32_bf16 v[124:127], v[140:143], v[184:187], v[124:127]
	v_mfma_f32_16x16x32_bf16 v[112:115], v[132:135], v[196:199], v[112:115]
	v_mfma_f32_16x16x32_bf16 v[108:111], v[140:143], v[196:199], v[108:111]
	v_mfma_f32_16x16x32_bf16 v[96:99], v[132:135], v[204:207], v[96:99]
	v_mfma_f32_16x16x32_bf16 v[92:95], v[140:143], v[204:207], v[92:95]
	v_mfma_f32_16x16x32_bf16 v[80:83], v[132:135], v[234:237], v[80:83]
	v_mfma_f32_16x16x32_bf16 v[76:79], v[140:143], v[234:237], v[76:79]
	v_mfma_f32_16x16x32_bf16 v[128:131], v[136:139], v[188:191], v[128:131]
	v_mfma_f32_16x16x32_bf16 v[124:127], v[144:147], v[188:191], v[124:127]
	v_mfma_f32_16x16x32_bf16 v[112:115], v[136:139], v[200:203], v[112:115]
	v_mfma_f32_16x16x32_bf16 v[108:111], v[144:147], v[200:203], v[108:111]
	v_mfma_f32_16x16x32_bf16 v[96:99], v[136:139], v[208:211], v[96:99]
	v_mfma_f32_16x16x32_bf16 v[92:95], v[144:147], v[208:211], v[92:95]
	v_mfma_f32_16x16x32_bf16 v[80:83], v[136:139], v[238:241], v[80:83]
	v_mfma_f32_16x16x32_bf16 v[76:79], v[144:147], v[238:241], v[76:79]
	s_setprio 0
	s_setprio 1
	v_mfma_f32_16x16x32_bf16 v[120:123], v[148:151], v[184:187], v[120:123]
	v_mfma_f32_16x16x32_bf16 v[116:119], v[176:179], v[184:187], v[116:119]
	v_mfma_f32_16x16x32_bf16 v[104:107], v[148:151], v[196:199], v[104:107]
	v_mfma_f32_16x16x32_bf16 v[100:103], v[176:179], v[196:199], v[100:103]
	v_mfma_f32_16x16x32_bf16 v[88:91], v[148:151], v[204:207], v[88:91]
	v_mfma_f32_16x16x32_bf16 v[84:87], v[176:179], v[204:207], v[84:87]
	v_mfma_f32_16x16x32_bf16 v[72:75], v[148:151], v[234:237], v[72:75]
	v_mfma_f32_16x16x32_bf16 v[68:71], v[176:179], v[234:237], v[68:71]
	v_mfma_f32_16x16x32_bf16 v[120:123], v[152:155], v[188:191], v[120:123]
	v_mfma_f32_16x16x32_bf16 v[116:119], v[180:183], v[188:191], v[116:119]
	v_mfma_f32_16x16x32_bf16 v[104:107], v[152:155], v[200:203], v[104:107]
	v_mfma_f32_16x16x32_bf16 v[100:103], v[180:183], v[200:203], v[100:103]
	v_mfma_f32_16x16x32_bf16 v[88:91], v[152:155], v[208:211], v[88:91]
	v_mfma_f32_16x16x32_bf16 v[84:87], v[180:183], v[208:211], v[84:87]
	v_mfma_f32_16x16x32_bf16 v[72:75], v[152:155], v[238:241], v[72:75]
	v_mfma_f32_16x16x32_bf16 v[68:71], v[180:183], v[238:241], v[68:71]
	s_setprio 0
	s_barrier
	s_add_i32 s48, s62, s52
	v_lshl_add_u64 v[166:167], v[166:167], 0, s[16:17]
	s_mov_b32 m0, s48
	ds_read_b128 v[184:187], v194 offset:49152
	ds_read_b128 v[188:191], v194 offset:50176
	ds_read_b128 v[196:199], v194 offset:51200
	ds_read_b128 v[200:203], v194 offset:52224
	ds_read_b128 v[204:207], v194 offset:53248
	ds_read_b128 v[208:211], v194 offset:54272
	ds_read_b128 v[234:237], v194 offset:55296
	ds_read_b128 v[238:241], v194 offset:56320
	s_add_i32 m0, s48, 0x2000
	s_add_u32 s46, s46, 0x40080
	v_lshl_add_u64 v[166:167], v[212:213], 0, s[16:17]
	s_addc_u32 s47, s47, 0
	s_add_i32 s48, s63, s52
	v_lshl_add_u64 v[166:167], s[46:47], 0, v[2:3]
	s_mov_b32 m0, s48
	s_nop 0
	v_lshl_add_u64 v[166:167], s[46:47], 0, v[156:157]
	s_add_i32 m0, s48, 0x2000
	s_nop 0
	v_lshl_add_u64 v[166:167], v[242:243], 0, s[16:17]
	s_mov_b32 m0, s34
	s_nop 0
	v_lshl_add_u64 v[166:167], v[244:245], 0, s[16:17]
	s_mov_b32 m0, s57
	s_nop 0
	s_waitcnt vmcnt(0)
	s_waitcnt lgkmcnt(0)
	s_barrier
	s_setprio 1
	s_waitcnt lgkmcnt(0)
	v_mfma_f32_16x16x32_bf16 v[64:67], v[132:135], v[184:187], v[64:67]
	v_mfma_f32_16x16x32_bf16 v[60:63], v[140:143], v[184:187], v[60:63]
	v_mfma_f32_16x16x32_bf16 v[48:51], v[132:135], v[196:199], v[48:51]
	v_mfma_f32_16x16x32_bf16 v[44:47], v[140:143], v[196:199], v[44:47]
	v_mfma_f32_16x16x32_bf16 v[32:35], v[132:135], v[204:207], v[32:35]
	v_mfma_f32_16x16x32_bf16 v[28:31], v[140:143], v[204:207], v[28:31]
	v_mfma_f32_16x16x32_bf16 v[16:19], v[132:135], v[234:237], v[16:19]
	v_mfma_f32_16x16x32_bf16 v[12:15], v[140:143], v[234:237], v[12:15]
	v_mfma_f32_16x16x32_bf16 v[64:67], v[136:139], v[188:191], v[64:67]
	v_mfma_f32_16x16x32_bf16 v[60:63], v[144:147], v[188:191], v[60:63]
	v_mfma_f32_16x16x32_bf16 v[48:51], v[136:139], v[200:203], v[48:51]
	v_mfma_f32_16x16x32_bf16 v[44:47], v[144:147], v[200:203], v[44:47]
	v_mfma_f32_16x16x32_bf16 v[32:35], v[136:139], v[208:211], v[32:35]
	v_mfma_f32_16x16x32_bf16 v[28:31], v[144:147], v[208:211], v[28:31]
	v_mfma_f32_16x16x32_bf16 v[16:19], v[136:139], v[238:241], v[16:19]
	v_mfma_f32_16x16x32_bf16 v[12:15], v[144:147], v[238:241], v[12:15]
	s_setprio 0
	s_setprio 1
	v_mfma_f32_16x16x32_bf16 v[56:59], v[148:151], v[184:187], v[56:59]
	v_mfma_f32_16x16x32_bf16 v[52:55], v[176:179], v[184:187], v[52:55]
	v_mfma_f32_16x16x32_bf16 v[40:43], v[148:151], v[196:199], v[40:43]
	v_mfma_f32_16x16x32_bf16 v[36:39], v[176:179], v[196:199], v[36:39]
	v_mfma_f32_16x16x32_bf16 v[24:27], v[148:151], v[204:207], v[24:27]
	v_mfma_f32_16x16x32_bf16 v[20:23], v[176:179], v[204:207], v[20:23]
	v_mfma_f32_16x16x32_bf16 v[8:11], v[148:151], v[234:237], v[8:11]
	v_mfma_f32_16x16x32_bf16 v[4:7], v[176:179], v[234:237], v[4:7]
	v_mfma_f32_16x16x32_bf16 v[56:59], v[152:155], v[188:191], v[56:59]
	v_mfma_f32_16x16x32_bf16 v[52:55], v[180:183], v[188:191], v[52:55]
	v_mfma_f32_16x16x32_bf16 v[40:43], v[152:155], v[200:203], v[40:43]
	v_mfma_f32_16x16x32_bf16 v[36:39], v[180:183], v[200:203], v[36:39]
	v_mfma_f32_16x16x32_bf16 v[24:27], v[152:155], v[208:211], v[24:27]
	v_mfma_f32_16x16x32_bf16 v[20:23], v[180:183], v[208:211], v[20:23]
	v_mfma_f32_16x16x32_bf16 v[8:11], v[152:155], v[238:241], v[8:11]
	v_mfma_f32_16x16x32_bf16 v[4:7], v[180:183], v[238:241], v[4:7]
	s_setprio 0
	s_barrier
	s_add_i32 s61, s61, 2
	s_add_u32 s30, s30, 0x100
	s_addc_u32 s31, s31, 0
	s_add_u32 s59, s59, 0x100
	s_addc_u32 s60, s60, 0
	s_cmp_gt_u32 s61, 13
	s_and_b64 vcc, exec, s[8:9]
	s_cbranch_vccz .LBB0_777
	s_barrier

.LBB0_999:
	s_add_u32 s4, s6, 0x100
	s_addc_u32 s5, s7, 0
	s_add_i32 s70, 0, 0x10000
	s_cmp_eq_u32 s69, 40
	s_cselect_b32 s55, s51, s5
	s_cselect_b32 s54, s50, s4
	s_cselect_b32 s19, s53, s15
	s_cselect_b32 s18, s52, s14
	s_add_i32 s71, 0, 0x14000
	v_add_u32_e32 v144, s70, v194
	v_add_u32_e32 v178, s71, v194
	ds_read_b128 v[132:135], v144
	ds_read_b128 v[136:139], v144 offset:1024
	ds_read_b128 v[140:143], v144 offset:2048
	ds_read_b128 v[144:147], v144 offset:3072
	ds_read_b128 v[148:151], v178
	ds_read_b128 v[152:155], v178 offset:1024
	ds_read_b128 v[156:159], v178 offset:2048
	ds_read_b128 v[178:181], v178 offset:3072
	v_lshl_add_u64 v[238:239], s[6:7], 0, v[166:167]
	s_add_i32 m0, s61, 0xc000
	ds_read_b128 v[182:185], v196
	ds_read_b128 v[186:189], v196 offset:1024
	ds_read_b128 v[190:193], v196 offset:2048
	ds_read_b128 v[198:201], v196 offset:3072
	ds_read_b128 v[202:205], v196 offset:4096
	ds_read_b128 v[206:209], v196 offset:5120
	ds_read_b128 v[210:213], v196 offset:6144
	ds_read_b128 v[234:237], v196 offset:7168
	global_load_lds_dwordx4 v[238:239], off
	v_lshl_add_u64 v[238:239], s[6:7], 0, v[176:177]
	s_add_i32 m0, s61, 0xe000
	s_nop 0
	global_load_lds_dwordx4 v[238:239], off
	s_waitcnt vmcnt(8)
	s_waitcnt lgkmcnt(0)
	s_barrier
	s_setprio 1
	s_waitcnt lgkmcnt(0)
	v_mfma_f32_16x16x32_bf16 v[128:131], v[132:135], v[182:185], v[128:131]
	v_mfma_f32_16x16x32_bf16 v[124:127], v[140:143], v[182:185], v[124:127]
	v_mfma_f32_16x16x32_bf16 v[112:115], v[132:135], v[190:193], v[112:115]
	v_mfma_f32_16x16x32_bf16 v[108:111], v[140:143], v[190:193], v[108:111]
	v_mfma_f32_16x16x32_bf16 v[96:99], v[132:135], v[202:205], v[96:99]
	v_mfma_f32_16x16x32_bf16 v[92:95], v[140:143], v[202:205], v[92:95]
	v_mfma_f32_16x16x32_bf16 v[80:83], v[132:135], v[210:213], v[80:83]
	v_mfma_f32_16x16x32_bf16 v[76:79], v[140:143], v[210:213], v[76:79]
	v_mfma_f32_16x16x32_bf16 v[128:131], v[136:139], v[186:189], v[128:131]
	v_mfma_f32_16x16x32_bf16 v[124:127], v[144:147], v[186:189], v[124:127]
	v_mfma_f32_16x16x32_bf16 v[112:115], v[136:139], v[198:201], v[112:115]
	v_mfma_f32_16x16x32_bf16 v[108:111], v[144:147], v[198:201], v[108:111]
	v_mfma_f32_16x16x32_bf16 v[96:99], v[136:139], v[206:209], v[96:99]
	v_mfma_f32_16x16x32_bf16 v[92:95], v[144:147], v[206:209], v[92:95]
	v_mfma_f32_16x16x32_bf16 v[80:83], v[136:139], v[234:237], v[80:83]
	v_mfma_f32_16x16x32_bf16 v[76:79], v[144:147], v[234:237], v[76:79]
	s_setprio 0
	s_setprio 1
	v_mfma_f32_16x16x32_bf16 v[120:123], v[148:151], v[182:185], v[120:123]
	v_mfma_f32_16x16x32_bf16 v[116:119], v[156:159], v[182:185], v[116:119]
	v_mfma_f32_16x16x32_bf16 v[104:107], v[148:151], v[190:193], v[104:107]
	v_mfma_f32_16x16x32_bf16 v[100:103], v[156:159], v[190:193], v[100:103]
	v_mfma_f32_16x16x32_bf16 v[88:91], v[148:151], v[202:205], v[88:91]
	v_mfma_f32_16x16x32_bf16 v[84:87], v[156:159], v[202:205], v[84:87]
	v_mfma_f32_16x16x32_bf16 v[72:75], v[148:151], v[210:213], v[72:75]
	v_mfma_f32_16x16x32_bf16 v[68:71], v[156:159], v[210:213], v[68:71]
	v_mfma_f32_16x16x32_bf16 v[120:123], v[152:155], v[186:189], v[120:123]
	v_mfma_f32_16x16x32_bf16 v[116:119], v[178:181], v[186:189], v[116:119]
	v_mfma_f32_16x16x32_bf16 v[104:107], v[152:155], v[198:201], v[104:107]
	v_mfma_f32_16x16x32_bf16 v[100:103], v[178:181], v[198:201], v[100:103]
	v_mfma_f32_16x16x32_bf16 v[88:91], v[152:155], v[206:209], v[88:91]
	v_mfma_f32_16x16x32_bf16 v[84:87], v[178:181], v[206:209], v[84:87]
	v_mfma_f32_16x16x32_bf16 v[72:75], v[152:155], v[234:237], v[72:75]
	v_mfma_f32_16x16x32_bf16 v[68:71], v[178:181], v[234:237], v[68:71]
	s_setprio 0
	s_barrier
	s_add_i32 s6, s70, s56
	v_lshl_add_u64 v[238:239], s[18:19], 0, v[2:3]
	s_mov_b32 m0, s6
	ds_read_b128 v[182:185], v196 offset:16384
	ds_read_b128 v[186:189], v196 offset:17408
	ds_read_b128 v[190:193], v196 offset:18432
	ds_read_b128 v[198:201], v196 offset:19456
	ds_read_b128 v[202:205], v196 offset:20480
	ds_read_b128 v[206:209], v196 offset:21504
	ds_read_b128 v[210:213], v196 offset:22528
	ds_read_b128 v[234:237], v196 offset:23552
	global_load_lds_dwordx4 v[238:239], off
	s_add_i32 m0, s6, 0x2000
	s_add_u32 s6, s18, 0xb0000
	v_lshl_add_u64 v[240:241], s[18:19], 0, v[160:161]
	s_addc_u32 s7, s19, 0
	s_add_i32 s70, s71, s56
	global_load_lds_dwordx4 v[240:241], off
	v_lshl_add_u64 v[242:243], s[6:7], 0, v[2:3]
	s_mov_b32 m0, s70
	v_lshl_add_u64 v[244:245], s[54:55], 0, v[162:163]
	global_load_lds_dwordx4 v[242:243], off
	v_lshl_add_u64 v[242:243], s[6:7], 0, v[160:161]
	s_add_i32 m0, s70, 0x2000
	s_nop 0
	global_load_lds_dwordx4 v[242:243], off
	v_lshl_add_u64 v[242:243], s[54:55], 0, v[164:165]
	s_mov_b32 m0, s61
	s_nop 0
	global_load_lds_dwordx4 v[242:243], off
	s_mov_b32 m0, s62
	s_nop 0
	global_load_lds_dwordx4 v[244:245], off
	s_waitcnt vmcnt(8)
	s_waitcnt lgkmcnt(0)
	s_barrier
	s_setprio 1
	s_waitcnt lgkmcnt(0)
	v_mfma_f32_16x16x32_bf16 v[64:67], v[132:135], v[182:185], v[64:67]
	v_mfma_f32_16x16x32_bf16 v[60:63], v[140:143], v[182:185], v[60:63]
	v_mfma_f32_16x16x32_bf16 v[48:51], v[132:135], v[190:193], v[48:51]
	v_mfma_f32_16x16x32_bf16 v[44:47], v[140:143], v[190:193], v[44:47]
	v_mfma_f32_16x16x32_bf16 v[32:35], v[132:135], v[202:205], v[32:35]
	v_mfma_f32_16x16x32_bf16 v[28:31], v[140:143], v[202:205], v[28:31]
	v_mfma_f32_16x16x32_bf16 v[16:19], v[132:135], v[210:213], v[16:19]
	v_mfma_f32_16x16x32_bf16 v[12:15], v[140:143], v[210:213], v[12:15]
	v_mfma_f32_16x16x32_bf16 v[64:67], v[136:139], v[186:189], v[64:67]
	v_mfma_f32_16x16x32_bf16 v[60:63], v[144:147], v[186:189], v[60:63]
	v_mfma_f32_16x16x32_bf16 v[48:51], v[136:139], v[198:201], v[48:51]
	v_mfma_f32_16x16x32_bf16 v[44:47], v[144:147], v[198:201], v[44:47]
	v_mfma_f32_16x16x32_bf16 v[32:35], v[136:139], v[206:209], v[32:35]
	v_mfma_f32_16x16x32_bf16 v[28:31], v[144:147], v[206:209], v[28:31]
	v_mfma_f32_16x16x32_bf16 v[16:19], v[136:139], v[234:237], v[16:19]
	v_mfma_f32_16x16x32_bf16 v[12:15], v[144:147], v[234:237], v[12:15]
	s_setprio 0
	s_setprio 1
	v_mfma_f32_16x16x32_bf16 v[56:59], v[148:151], v[182:185], v[56:59]
	v_mfma_f32_16x16x32_bf16 v[52:55], v[156:159], v[182:185], v[52:55]
	v_mfma_f32_16x16x32_bf16 v[40:43], v[148:151], v[190:193], v[40:43]
	v_mfma_f32_16x16x32_bf16 v[36:39], v[156:159], v[190:193], v[36:39]
	v_mfma_f32_16x16x32_bf16 v[24:27], v[148:151], v[202:205], v[24:27]
	v_mfma_f32_16x16x32_bf16 v[20:23], v[156:159], v[202:205], v[20:23]
	v_mfma_f32_16x16x32_bf16 v[8:11], v[148:151], v[210:213], v[8:11]
	v_mfma_f32_16x16x32_bf16 v[4:7], v[156:159], v[210:213], v[4:7]
	v_mfma_f32_16x16x32_bf16 v[56:59], v[152:155], v[186:189], v[56:59]
	v_mfma_f32_16x16x32_bf16 v[52:55], v[178:181], v[186:189], v[52:55]
	v_mfma_f32_16x16x32_bf16 v[40:43], v[152:155], v[198:201], v[40:43]
	v_mfma_f32_16x16x32_bf16 v[36:39], v[178:181], v[198:201], v[36:39]
	v_mfma_f32_16x16x32_bf16 v[24:27], v[152:155], v[206:209], v[24:27]
	v_mfma_f32_16x16x32_bf16 v[20:23], v[178:181], v[206:209], v[20:23]
	v_mfma_f32_16x16x32_bf16 v[8:11], v[152:155], v[234:237], v[8:11]
	v_mfma_f32_16x16x32_bf16 v[4:7], v[178:181], v[234:237], v[4:7]
	s_setprio 0
	s_barrier
	s_add_i32 s70, 0, 0x18000
	s_add_i32 s71, 0, 0x1c000
	v_add_u32_e32 v144, s70, v194
	v_add_u32_e32 v178, s71, v194
	ds_read_b128 v[132:135], v144
	ds_read_b128 v[136:139], v144 offset:1024
	ds_read_b128 v[140:143], v144 offset:2048
	ds_read_b128 v[144:147], v144 offset:3072
	ds_read_b128 v[148:151], v178
	ds_read_b128 v[152:155], v178 offset:1024
	ds_read_b128 v[156:159], v178 offset:2048
	ds_read_b128 v[178:181], v178 offset:3072
	s_add_u32 s6, s54, 0xb0000
	s_addc_u32 s7, s55, 0
	s_mov_b32 m0, s63
	v_lshl_add_u64 v[246:247], s[6:7], 0, v[164:165]
	ds_read_b128 v[182:185], v196 offset:32768
	ds_read_b128 v[186:189], v196 offset:33792
	ds_read_b128 v[190:193], v196 offset:34816
	ds_read_b128 v[198:201], v196 offset:35840
	ds_read_b128 v[202:205], v196 offset:36864
	ds_read_b128 v[206:209], v196 offset:37888
	ds_read_b128 v[210:213], v196 offset:38912
	ds_read_b128 v[234:237], v196 offset:39936
	global_load_lds_dwordx4 v[246:247], off
	v_lshl_add_u64 v[246:247], s[6:7], 0, v[162:163]
	s_mov_b32 m0, s64
	s_nop 0
	global_load_lds_dwordx4 v[246:247], off
	s_waitcnt vmcnt(8)
	s_waitcnt lgkmcnt(0)
	s_barrier
	s_setprio 1
	s_waitcnt lgkmcnt(0)
	v_mfma_f32_16x16x32_bf16 v[128:131], v[132:135], v[182:185], v[128:131]
	v_mfma_f32_16x16x32_bf16 v[124:127], v[140:143], v[182:185], v[124:127]
	v_mfma_f32_16x16x32_bf16 v[112:115], v[132:135], v[190:193], v[112:115]
	v_mfma_f32_16x16x32_bf16 v[108:111], v[140:143], v[190:193], v[108:111]
	v_mfma_f32_16x16x32_bf16 v[96:99], v[132:135], v[202:205], v[96:99]
	v_mfma_f32_16x16x32_bf16 v[92:95], v[140:143], v[202:205], v[92:95]
	v_mfma_f32_16x16x32_bf16 v[80:83], v[132:135], v[210:213], v[80:83]
	v_mfma_f32_16x16x32_bf16 v[76:79], v[140:143], v[210:213], v[76:79]
	v_mfma_f32_16x16x32_bf16 v[128:131], v[136:139], v[186:189], v[128:131]
	v_mfma_f32_16x16x32_bf16 v[124:127], v[144:147], v[186:189], v[124:127]
	v_mfma_f32_16x16x32_bf16 v[112:115], v[136:139], v[198:201], v[112:115]
	v_mfma_f32_16x16x32_bf16 v[108:111], v[144:147], v[198:201], v[108:111]
	v_mfma_f32_16x16x32_bf16 v[96:99], v[136:139], v[206:209], v[96:99]
	v_mfma_f32_16x16x32_bf16 v[92:95], v[144:147], v[206:209], v[92:95]
	v_mfma_f32_16x16x32_bf16 v[80:83], v[136:139], v[234:237], v[80:83]
	v_mfma_f32_16x16x32_bf16 v[76:79], v[144:147], v[234:237], v[76:79]
	s_setprio 0
	s_setprio 1
	v_mfma_f32_16x16x32_bf16 v[120:123], v[148:151], v[182:185], v[120:123]
	v_mfma_f32_16x16x32_bf16 v[116:119], v[156:159], v[182:185], v[116:119]
	v_mfma_f32_16x16x32_bf16 v[104:107], v[148:151], v[190:193], v[104:107]
	v_mfma_f32_16x16x32_bf16 v[100:103], v[156:159], v[190:193], v[100:103]
	v_mfma_f32_16x16x32_bf16 v[88:91], v[148:151], v[202:205], v[88:91]
	v_mfma_f32_16x16x32_bf16 v[84:87], v[156:159], v[202:205], v[84:87]
	v_mfma_f32_16x16x32_bf16 v[72:75], v[148:151], v[210:213], v[72:75]
	v_mfma_f32_16x16x32_bf16 v[68:71], v[156:159], v[210:213], v[68:71]
	v_mfma_f32_16x16x32_bf16 v[120:123], v[152:155], v[186:189], v[120:123]
	v_mfma_f32_16x16x32_bf16 v[116:119], v[178:181], v[186:189], v[116:119]
	v_mfma_f32_16x16x32_bf16 v[104:107], v[152:155], v[198:201], v[104:107]
	v_mfma_f32_16x16x32_bf16 v[100:103], v[178:181], v[198:201], v[100:103]
	v_mfma_f32_16x16x32_bf16 v[88:91], v[152:155], v[206:209], v[88:91]
	v_mfma_f32_16x16x32_bf16 v[84:87], v[178:181], v[206:209], v[84:87]
	v_mfma_f32_16x16x32_bf16 v[72:75], v[152:155], v[234:237], v[72:75]
	v_mfma_f32_16x16x32_bf16 v[68:71], v[178:181], v[234:237], v[68:71]
	s_setprio 0
	s_barrier
	s_add_i32 s6, s70, s56
	v_lshl_add_u64 v[238:239], v[238:239], 0, s[16:17]
	s_mov_b32 m0, s6
	ds_read_b128 v[182:185], v196 offset:49152
	ds_read_b128 v[186:189], v196 offset:50176
	ds_read_b128 v[190:193], v196 offset:51200
	ds_read_b128 v[198:201], v196 offset:52224
	ds_read_b128 v[202:205], v196 offset:53248
	ds_read_b128 v[206:209], v196 offset:54272
	ds_read_b128 v[210:213], v196 offset:55296
	ds_read_b128 v[234:237], v196 offset:56320
	global_load_lds_dwordx4 v[238:239], off
	s_add_i32 m0, s6, 0x2000
	s_add_u32 s6, s18, 0xb0080
	v_lshl_add_u64 v[238:239], v[240:241], 0, s[16:17]
	s_addc_u32 s7, s19, 0
	s_add_i32 s18, s71, s56
	global_load_lds_dwordx4 v[238:239], off
	v_lshl_add_u64 v[238:239], s[6:7], 0, v[2:3]
	s_mov_b32 m0, s18
	s_nop 0
	global_load_lds_dwordx4 v[238:239], off
	v_lshl_add_u64 v[238:239], s[6:7], 0, v[160:161]
	s_add_i32 m0, s18, 0x2000
	s_nop 0
	global_load_lds_dwordx4 v[238:239], off
	v_lshl_add_u64 v[238:239], v[242:243], 0, s[16:17]
	s_mov_b32 m0, s34
	s_nop 0
	global_load_lds_dwordx4 v[238:239], off
	v_lshl_add_u64 v[238:239], v[244:245], 0, s[16:17]
	s_mov_b32 m0, s65
	s_nop 0
	global_load_lds_dwordx4 v[238:239], off
	s_waitcnt vmcnt(8)
	s_waitcnt lgkmcnt(0)
	s_barrier
	s_setprio 1
	s_waitcnt lgkmcnt(0)
	v_mfma_f32_16x16x32_bf16 v[64:67], v[132:135], v[182:185], v[64:67]
	v_mfma_f32_16x16x32_bf16 v[60:63], v[140:143], v[182:185], v[60:63]
	v_mfma_f32_16x16x32_bf16 v[48:51], v[132:135], v[190:193], v[48:51]
	v_mfma_f32_16x16x32_bf16 v[44:47], v[140:143], v[190:193], v[44:47]
	v_mfma_f32_16x16x32_bf16 v[32:35], v[132:135], v[202:205], v[32:35]
	v_mfma_f32_16x16x32_bf16 v[28:31], v[140:143], v[202:205], v[28:31]
	v_mfma_f32_16x16x32_bf16 v[16:19], v[132:135], v[210:213], v[16:19]
	v_mfma_f32_16x16x32_bf16 v[12:15], v[140:143], v[210:213], v[12:15]
	v_mfma_f32_16x16x32_bf16 v[64:67], v[136:139], v[186:189], v[64:67]
	v_mfma_f32_16x16x32_bf16 v[60:63], v[144:147], v[186:189], v[60:63]
	v_mfma_f32_16x16x32_bf16 v[48:51], v[136:139], v[198:201], v[48:51]
	v_mfma_f32_16x16x32_bf16 v[44:47], v[144:147], v[198:201], v[44:47]
	v_mfma_f32_16x16x32_bf16 v[32:35], v[136:139], v[206:209], v[32:35]
	v_mfma_f32_16x16x32_bf16 v[28:31], v[144:147], v[206:209], v[28:31]
	v_mfma_f32_16x16x32_bf16 v[16:19], v[136:139], v[234:237], v[16:19]
	v_mfma_f32_16x16x32_bf16 v[12:15], v[144:147], v[234:237], v[12:15]
	s_setprio 0
	s_setprio 1
	v_mfma_f32_16x16x32_bf16 v[56:59], v[148:151], v[182:185], v[56:59]
	v_mfma_f32_16x16x32_bf16 v[52:55], v[156:159], v[182:185], v[52:55]
	v_mfma_f32_16x16x32_bf16 v[40:43], v[148:151], v[190:193], v[40:43]
	v_mfma_f32_16x16x32_bf16 v[36:39], v[156:159], v[190:193], v[36:39]
	v_mfma_f32_16x16x32_bf16 v[24:27], v[148:151], v[202:205], v[24:27]
	v_mfma_f32_16x16x32_bf16 v[20:23], v[156:159], v[202:205], v[20:23]
	v_mfma_f32_16x16x32_bf16 v[8:11], v[148:151], v[210:213], v[8:11]
	v_mfma_f32_16x16x32_bf16 v[4:7], v[156:159], v[210:213], v[4:7]
	v_mfma_f32_16x16x32_bf16 v[56:59], v[152:155], v[186:189], v[56:59]
	v_mfma_f32_16x16x32_bf16 v[52:55], v[178:181], v[186:189], v[52:55]
	v_mfma_f32_16x16x32_bf16 v[40:43], v[152:155], v[198:201], v[40:43]
	v_mfma_f32_16x16x32_bf16 v[36:39], v[178:181], v[198:201], v[36:39]
	v_mfma_f32_16x16x32_bf16 v[24:27], v[152:155], v[206:209], v[24:27]
	v_mfma_f32_16x16x32_bf16 v[20:23], v[178:181], v[206:209], v[20:23]
	v_mfma_f32_16x16x32_bf16 v[8:11], v[152:155], v[234:237], v[8:11]
	v_mfma_f32_16x16x32_bf16 v[4:7], v[178:181], v[234:237], v[4:7]
	s_setprio 0
	s_barrier
	s_add_i32 s69, s69, 2
	s_add_u32 s14, s14, 0x100
	s_addc_u32 s15, s15, 0
	s_cmp_gt_u32 s69, 39
	s_mov_b64 s[6:7], s[4:5]
	s_cbranch_scc0 .LBB0_999
	s_add_u32 s4, s6, 0x100
	s_addc_u32 s5, s7, 0
	s_add_i32 s70, 0, 0x10000
	s_cmp_eq_u32 s69, 40
	s_cselect_b32 s55, s51, s5
	s_cselect_b32 s54, s50, s4
	s_cselect_b32 s19, s53, s15
	s_cselect_b32 s18, s52, s14
	s_add_i32 s71, 0, 0x14000
	v_add_u32_e32 v144, s70, v194
	v_add_u32_e32 v178, s71, v194
	ds_read_b128 v[132:135], v144
	ds_read_b128 v[136:139], v144 offset:1024
	ds_read_b128 v[140:143], v144 offset:2048
	ds_read_b128 v[144:147], v144 offset:3072
	ds_read_b128 v[148:151], v178
	ds_read_b128 v[152:155], v178 offset:1024
	ds_read_b128 v[156:159], v178 offset:2048
	ds_read_b128 v[178:181], v178 offset:3072
	v_lshl_add_u64 v[238:239], s[6:7], 0, v[166:167]
	s_add_i32 m0, s61, 0xc000
	ds_read_b128 v[182:185], v196
	ds_read_b128 v[186:189], v196 offset:1024
	ds_read_b128 v[190:193], v196 offset:2048
	ds_read_b128 v[198:201], v196 offset:3072
	ds_read_b128 v[202:205], v196 offset:4096
	ds_read_b128 v[206:209], v196 offset:5120
	ds_read_b128 v[210:213], v196 offset:6144
	ds_read_b128 v[234:237], v196 offset:7168
	global_load_lds_dwordx4 v[238:239], off
	v_lshl_add_u64 v[238:239], s[6:7], 0, v[176:177]
	s_add_i32 m0, s61, 0xe000
	s_nop 0
	global_load_lds_dwordx4 v[238:239], off
	s_waitcnt vmcnt(8)
	s_waitcnt lgkmcnt(0)
	s_barrier
	s_setprio 1
	s_waitcnt lgkmcnt(0)
	v_mfma_f32_16x16x32_bf16 v[128:131], v[132:135], v[182:185], v[128:131]
	v_mfma_f32_16x16x32_bf16 v[124:127], v[140:143], v[182:185], v[124:127]
	v_mfma_f32_16x16x32_bf16 v[112:115], v[132:135], v[190:193], v[112:115]
	v_mfma_f32_16x16x32_bf16 v[108:111], v[140:143], v[190:193], v[108:111]
	v_mfma_f32_16x16x32_bf16 v[96:99], v[132:135], v[202:205], v[96:99]
	v_mfma_f32_16x16x32_bf16 v[92:95], v[140:143], v[202:205], v[92:95]
	v_mfma_f32_16x16x32_bf16 v[80:83], v[132:135], v[210:213], v[80:83]
	v_mfma_f32_16x16x32_bf16 v[76:79], v[140:143], v[210:213], v[76:79]
	v_mfma_f32_16x16x32_bf16 v[128:131], v[136:139], v[186:189], v[128:131]
	v_mfma_f32_16x16x32_bf16 v[124:127], v[144:147], v[186:189], v[124:127]
	v_mfma_f32_16x16x32_bf16 v[112:115], v[136:139], v[198:201], v[112:115]
	v_mfma_f32_16x16x32_bf16 v[108:111], v[144:147], v[198:201], v[108:111]
	v_mfma_f32_16x16x32_bf16 v[96:99], v[136:139], v[206:209], v[96:99]
	v_mfma_f32_16x16x32_bf16 v[92:95], v[144:147], v[206:209], v[92:95]
	v_mfma_f32_16x16x32_bf16 v[80:83], v[136:139], v[234:237], v[80:83]
	v_mfma_f32_16x16x32_bf16 v[76:79], v[144:147], v[234:237], v[76:79]
	s_setprio 0
	s_setprio 1
	v_mfma_f32_16x16x32_bf16 v[120:123], v[148:151], v[182:185], v[120:123]
	v_mfma_f32_16x16x32_bf16 v[116:119], v[156:159], v[182:185], v[116:119]
	v_mfma_f32_16x16x32_bf16 v[104:107], v[148:151], v[190:193], v[104:107]
	v_mfma_f32_16x16x32_bf16 v[100:103], v[156:159], v[190:193], v[100:103]
	v_mfma_f32_16x16x32_bf16 v[88:91], v[148:151], v[202:205], v[88:91]
	v_mfma_f32_16x16x32_bf16 v[84:87], v[156:159], v[202:205], v[84:87]
	v_mfma_f32_16x16x32_bf16 v[72:75], v[148:151], v[210:213], v[72:75]
	v_mfma_f32_16x16x32_bf16 v[68:71], v[156:159], v[210:213], v[68:71]
	v_mfma_f32_16x16x32_bf16 v[120:123], v[152:155], v[186:189], v[120:123]
	v_mfma_f32_16x16x32_bf16 v[116:119], v[178:181], v[186:189], v[116:119]
	v_mfma_f32_16x16x32_bf16 v[104:107], v[152:155], v[198:201], v[104:107]
	v_mfma_f32_16x16x32_bf16 v[100:103], v[178:181], v[198:201], v[100:103]
	v_mfma_f32_16x16x32_bf16 v[88:91], v[152:155], v[206:209], v[88:91]
	v_mfma_f32_16x16x32_bf16 v[84:87], v[178:181], v[206:209], v[84:87]
	v_mfma_f32_16x16x32_bf16 v[72:75], v[152:155], v[234:237], v[72:75]
	v_mfma_f32_16x16x32_bf16 v[68:71], v[178:181], v[234:237], v[68:71]
	s_setprio 0
	s_barrier
	s_add_i32 s6, s70, s56
	v_lshl_add_u64 v[238:239], s[18:19], 0, v[2:3]
	s_mov_b32 m0, s6
	ds_read_b128 v[182:185], v196 offset:16384
	ds_read_b128 v[186:189], v196 offset:17408
	ds_read_b128 v[190:193], v196 offset:18432
	ds_read_b128 v[198:201], v196 offset:19456
	ds_read_b128 v[202:205], v196 offset:20480
	ds_read_b128 v[206:209], v196 offset:21504
	ds_read_b128 v[210:213], v196 offset:22528
	ds_read_b128 v[234:237], v196 offset:23552
	s_add_i32 m0, s6, 0x2000
	s_add_u32 s6, s18, 0xb0000
	v_lshl_add_u64 v[240:241], s[18:19], 0, v[160:161]
	s_addc_u32 s7, s19, 0
	s_add_i32 s70, s71, s56
	v_lshl_add_u64 v[242:243], s[6:7], 0, v[2:3]
	s_mov_b32 m0, s70
	v_lshl_add_u64 v[244:245], s[54:55], 0, v[162:163]
	v_lshl_add_u64 v[242:243], s[6:7], 0, v[160:161]
	s_add_i32 m0, s70, 0x2000
	s_nop 0
	v_lshl_add_u64 v[242:243], s[54:55], 0, v[164:165]
	s_mov_b32 m0, s61
	s_nop 0
	s_mov_b32 m0, s62
	s_nop 0
	s_waitcnt vmcnt(2)
	s_waitcnt lgkmcnt(0)
	s_barrier
	s_setprio 1
	s_waitcnt lgkmcnt(0)
	v_mfma_f32_16x16x32_bf16 v[64:67], v[132:135], v[182:185], v[64:67]
	v_mfma_f32_16x16x32_bf16 v[60:63], v[140:143], v[182:185], v[60:63]
	v_mfma_f32_16x16x32_bf16 v[48:51], v[132:135], v[190:193], v[48:51]
	v_mfma_f32_16x16x32_bf16 v[44:47], v[140:143], v[190:193], v[44:47]
	v_mfma_f32_16x16x32_bf16 v[32:35], v[132:135], v[202:205], v[32:35]
	v_mfma_f32_16x16x32_bf16 v[28:31], v[140:143], v[202:205], v[28:31]
	v_mfma_f32_16x16x32_bf16 v[16:19], v[132:135], v[210:213], v[16:19]
	v_mfma_f32_16x16x32_bf16 v[12:15], v[140:143], v[210:213], v[12:15]
	v_mfma_f32_16x16x32_bf16 v[64:67], v[136:139], v[186:189], v[64:67]
	v_mfma_f32_16x16x32_bf16 v[60:63], v[144:147], v[186:189], v[60:63]
	v_mfma_f32_16x16x32_bf16 v[48:51], v[136:139], v[198:201], v[48:51]
	v_mfma_f32_16x16x32_bf16 v[44:47], v[144:147], v[198:201], v[44:47]
	v_mfma_f32_16x16x32_bf16 v[32:35], v[136:139], v[206:209], v[32:35]
	v_mfma_f32_16x16x32_bf16 v[28:31], v[144:147], v[206:209], v[28:31]
	v_mfma_f32_16x16x32_bf16 v[16:19], v[136:139], v[234:237], v[16:19]
	v_mfma_f32_16x16x32_bf16 v[12:15], v[144:147], v[234:237], v[12:15]
	s_setprio 0
	s_setprio 1
	v_mfma_f32_16x16x32_bf16 v[56:59], v[148:151], v[182:185], v[56:59]
	v_mfma_f32_16x16x32_bf16 v[52:55], v[156:159], v[182:185], v[52:55]
	v_mfma_f32_16x16x32_bf16 v[40:43], v[148:151], v[190:193], v[40:43]
	v_mfma_f32_16x16x32_bf16 v[36:39], v[156:159], v[190:193], v[36:39]
	v_mfma_f32_16x16x32_bf16 v[24:27], v[148:151], v[202:205], v[24:27]
	v_mfma_f32_16x16x32_bf16 v[20:23], v[156:159], v[202:205], v[20:23]
	v_mfma_f32_16x16x32_bf16 v[8:11], v[148:151], v[210:213], v[8:11]
	v_mfma_f32_16x16x32_bf16 v[4:7], v[156:159], v[210:213], v[4:7]
	v_mfma_f32_16x16x32_bf16 v[56:59], v[152:155], v[186:189], v[56:59]
	v_mfma_f32_16x16x32_bf16 v[52:55], v[178:181], v[186:189], v[52:55]
	v_mfma_f32_16x16x32_bf16 v[40:43], v[152:155], v[198:201], v[40:43]
	v_mfma_f32_16x16x32_bf16 v[36:39], v[178:181], v[198:201], v[36:39]
	v_mfma_f32_16x16x32_bf16 v[24:27], v[152:155], v[206:209], v[24:27]
	v_mfma_f32_16x16x32_bf16 v[20:23], v[178:181], v[206:209], v[20:23]
	v_mfma_f32_16x16x32_bf16 v[8:11], v[152:155], v[234:237], v[8:11]
	v_mfma_f32_16x16x32_bf16 v[4:7], v[178:181], v[234:237], v[4:7]
	s_setprio 0
	s_barrier
	s_add_i32 s70, 0, 0x18000
	s_add_i32 s71, 0, 0x1c000
	v_add_u32_e32 v144, s70, v194
	v_add_u32_e32 v178, s71, v194
	ds_read_b128 v[132:135], v144
	ds_read_b128 v[136:139], v144 offset:1024
	ds_read_b128 v[140:143], v144 offset:2048
	ds_read_b128 v[144:147], v144 offset:3072
	ds_read_b128 v[148:151], v178
	ds_read_b128 v[152:155], v178 offset:1024
	ds_read_b128 v[156:159], v178 offset:2048
	ds_read_b128 v[178:181], v178 offset:3072
	s_add_u32 s6, s54, 0xb0000
	s_addc_u32 s7, s55, 0
	s_mov_b32 m0, s63
	v_lshl_add_u64 v[246:247], s[6:7], 0, v[164:165]
	ds_read_b128 v[182:185], v196 offset:32768
	ds_read_b128 v[186:189], v196 offset:33792
	ds_read_b128 v[190:193], v196 offset:34816
	ds_read_b128 v[198:201], v196 offset:35840
	ds_read_b128 v[202:205], v196 offset:36864
	ds_read_b128 v[206:209], v196 offset:37888
	ds_read_b128 v[210:213], v196 offset:38912
	ds_read_b128 v[234:237], v196 offset:39936
	v_lshl_add_u64 v[246:247], s[6:7], 0, v[162:163]
	s_mov_b32 m0, s64
	s_nop 0
	s_waitcnt vmcnt(0)
	s_waitcnt lgkmcnt(0)
	s_barrier
	s_setprio 1
	s_waitcnt lgkmcnt(0)
	v_mfma_f32_16x16x32_bf16 v[128:131], v[132:135], v[182:185], v[128:131]
	v_mfma_f32_16x16x32_bf16 v[124:127], v[140:143], v[182:185], v[124:127]
	v_mfma_f32_16x16x32_bf16 v[112:115], v[132:135], v[190:193], v[112:115]
	v_mfma_f32_16x16x32_bf16 v[108:111], v[140:143], v[190:193], v[108:111]
	v_mfma_f32_16x16x32_bf16 v[96:99], v[132:135], v[202:205], v[96:99]
	v_mfma_f32_16x16x32_bf16 v[92:95], v[140:143], v[202:205], v[92:95]
	v_mfma_f32_16x16x32_bf16 v[80:83], v[132:135], v[210:213], v[80:83]
	v_mfma_f32_16x16x32_bf16 v[76:79], v[140:143], v[210:213], v[76:79]
	v_mfma_f32_16x16x32_bf16 v[128:131], v[136:139], v[186:189], v[128:131]
	v_mfma_f32_16x16x32_bf16 v[124:127], v[144:147], v[186:189], v[124:127]
	v_mfma_f32_16x16x32_bf16 v[112:115], v[136:139], v[198:201], v[112:115]
	v_mfma_f32_16x16x32_bf16 v[108:111], v[144:147], v[198:201], v[108:111]
	v_mfma_f32_16x16x32_bf16 v[96:99], v[136:139], v[206:209], v[96:99]
	v_mfma_f32_16x16x32_bf16 v[92:95], v[144:147], v[206:209], v[92:95]
	v_mfma_f32_16x16x32_bf16 v[80:83], v[136:139], v[234:237], v[80:83]
	v_mfma_f32_16x16x32_bf16 v[76:79], v[144:147], v[234:237], v[76:79]
	s_setprio 0
	s_setprio 1
	v_mfma_f32_16x16x32_bf16 v[120:123], v[148:151], v[182:185], v[120:123]
	v_mfma_f32_16x16x32_bf16 v[116:119], v[156:159], v[182:185], v[116:119]
	v_mfma_f32_16x16x32_bf16 v[104:107], v[148:151], v[190:193], v[104:107]
	v_mfma_f32_16x16x32_bf16 v[100:103], v[156:159], v[190:193], v[100:103]
	v_mfma_f32_16x16x32_bf16 v[88:91], v[148:151], v[202:205], v[88:91]
	v_mfma_f32_16x16x32_bf16 v[84:87], v[156:159], v[202:205], v[84:87]
	v_mfma_f32_16x16x32_bf16 v[72:75], v[148:151], v[210:213], v[72:75]
	v_mfma_f32_16x16x32_bf16 v[68:71], v[156:159], v[210:213], v[68:71]
	v_mfma_f32_16x16x32_bf16 v[120:123], v[152:155], v[186:189], v[120:123]
	v_mfma_f32_16x16x32_bf16 v[116:119], v[178:181], v[186:189], v[116:119]
	v_mfma_f32_16x16x32_bf16 v[104:107], v[152:155], v[198:201], v[104:107]
	v_mfma_f32_16x16x32_bf16 v[100:103], v[178:181], v[198:201], v[100:103]
	v_mfma_f32_16x16x32_bf16 v[88:91], v[152:155], v[206:209], v[88:91]
	v_mfma_f32_16x16x32_bf16 v[84:87], v[178:181], v[206:209], v[84:87]
	v_mfma_f32_16x16x32_bf16 v[72:75], v[152:155], v[234:237], v[72:75]
	v_mfma_f32_16x16x32_bf16 v[68:71], v[178:181], v[234:237], v[68:71]
	s_setprio 0
	s_barrier
	s_add_i32 s6, s70, s56
	v_lshl_add_u64 v[238:239], v[238:239], 0, s[16:17]
	s_mov_b32 m0, s6
	ds_read_b128 v[182:185], v196 offset:49152
	ds_read_b128 v[186:189], v196 offset:50176
	ds_read_b128 v[190:193], v196 offset:51200
	ds_read_b128 v[198:201], v196 offset:52224
	ds_read_b128 v[202:205], v196 offset:53248
	ds_read_b128 v[206:209], v196 offset:54272
	ds_read_b128 v[210:213], v196 offset:55296
	ds_read_b128 v[234:237], v196 offset:56320
	s_add_i32 m0, s6, 0x2000
	s_add_u32 s6, s18, 0xb0080
	v_lshl_add_u64 v[238:239], v[240:241], 0, s[16:17]
	s_addc_u32 s7, s19, 0
	s_add_i32 s18, s71, s56
	v_lshl_add_u64 v[238:239], s[6:7], 0, v[2:3]
	s_mov_b32 m0, s18
	s_nop 0
	v_lshl_add_u64 v[238:239], s[6:7], 0, v[160:161]
	s_add_i32 m0, s18, 0x2000
	s_nop 0
	v_lshl_add_u64 v[238:239], v[242:243], 0, s[16:17]
	s_mov_b32 m0, s34
	s_nop 0
	v_lshl_add_u64 v[238:239], v[244:245], 0, s[16:17]
	s_mov_b32 m0, s65
	s_nop 0
	s_waitcnt vmcnt(0)
	s_waitcnt lgkmcnt(0)
	s_barrier
	s_setprio 1
	s_waitcnt lgkmcnt(0)
	v_mfma_f32_16x16x32_bf16 v[64:67], v[132:135], v[182:185], v[64:67]
	v_mfma_f32_16x16x32_bf16 v[60:63], v[140:143], v[182:185], v[60:63]
	v_mfma_f32_16x16x32_bf16 v[48:51], v[132:135], v[190:193], v[48:51]
	v_mfma_f32_16x16x32_bf16 v[44:47], v[140:143], v[190:193], v[44:47]
	v_mfma_f32_16x16x32_bf16 v[32:35], v[132:135], v[202:205], v[32:35]
	v_mfma_f32_16x16x32_bf16 v[28:31], v[140:143], v[202:205], v[28:31]
	v_mfma_f32_16x16x32_bf16 v[16:19], v[132:135], v[210:213], v[16:19]
	v_mfma_f32_16x16x32_bf16 v[12:15], v[140:143], v[210:213], v[12:15]
	v_mfma_f32_16x16x32_bf16 v[64:67], v[136:139], v[186:189], v[64:67]
	v_mfma_f32_16x16x32_bf16 v[60:63], v[144:147], v[186:189], v[60:63]
	v_mfma_f32_16x16x32_bf16 v[48:51], v[136:139], v[198:201], v[48:51]
	v_mfma_f32_16x16x32_bf16 v[44:47], v[144:147], v[198:201], v[44:47]
	v_mfma_f32_16x16x32_bf16 v[32:35], v[136:139], v[206:209], v[32:35]
	v_mfma_f32_16x16x32_bf16 v[28:31], v[144:147], v[206:209], v[28:31]
	v_mfma_f32_16x16x32_bf16 v[16:19], v[136:139], v[234:237], v[16:19]
	v_mfma_f32_16x16x32_bf16 v[12:15], v[144:147], v[234:237], v[12:15]
	s_setprio 0
	s_setprio 1
	v_mfma_f32_16x16x32_bf16 v[56:59], v[148:151], v[182:185], v[56:59]
	v_mfma_f32_16x16x32_bf16 v[52:55], v[156:159], v[182:185], v[52:55]
	v_mfma_f32_16x16x32_bf16 v[40:43], v[148:151], v[190:193], v[40:43]
	v_mfma_f32_16x16x32_bf16 v[36:39], v[156:159], v[190:193], v[36:39]
	v_mfma_f32_16x16x32_bf16 v[24:27], v[148:151], v[202:205], v[24:27]
	v_mfma_f32_16x16x32_bf16 v[20:23], v[156:159], v[202:205], v[20:23]
	v_mfma_f32_16x16x32_bf16 v[8:11], v[148:151], v[210:213], v[8:11]
	v_mfma_f32_16x16x32_bf16 v[4:7], v[156:159], v[210:213], v[4:7]
	v_mfma_f32_16x16x32_bf16 v[56:59], v[152:155], v[186:189], v[56:59]
	v_mfma_f32_16x16x32_bf16 v[52:55], v[178:181], v[186:189], v[52:55]
	v_mfma_f32_16x16x32_bf16 v[40:43], v[152:155], v[198:201], v[40:43]
	v_mfma_f32_16x16x32_bf16 v[36:39], v[178:181], v[198:201], v[36:39]
	v_mfma_f32_16x16x32_bf16 v[24:27], v[152:155], v[206:209], v[24:27]
	v_mfma_f32_16x16x32_bf16 v[20:23], v[178:181], v[206:209], v[20:23]
	v_mfma_f32_16x16x32_bf16 v[8:11], v[152:155], v[234:237], v[8:11]
	v_mfma_f32_16x16x32_bf16 v[4:7], v[178:181], v[234:237], v[4:7]
	s_setprio 0
	s_barrier
	s_add_i32 s69, s69, 2
	s_add_u32 s14, s14, 0x100
	s_addc_u32 s15, s15, 0
	s_cmp_gt_u32 s69, 41
	s_mov_b64 s[6:7], s[4:5]
	s_and_b64 vcc, exec, s[30:31]
	s_cbranch_vccz .LBB0_1002
	s_barrier
